# DIFF: next-tile LDS-DMA issue spread over QK(sub0), QK(sub1) and first half of PV(sub0)
# baseline (speedup 1.0000x reference)
; #define MFMA(a, b, c) __builtin_amdgcn_mfma_f32_32x32x16_bf16((a), (b), (c), 0, 0, 0)
; #define GLDS16(g, l) __builtin_amdgcn_global_load_lds((const unsigned*)(g), (unsigned*)(l), 16, 0, 0)
; #define GLDS4(g, l) __builtin_amdgcn_global_load_lds((const unsigned*)(g), (unsigned*)(l), 4, 0, 0)
; DI int tid_pinned() { int t = threadIdx.x; asm volatile("" : "+v"(t)); return t; }
; DI f32x16 zero16() { f32x16 z; for (int r = 0; r < 16; ++r) z[r] = 0.f; return z; }
; #define DIFF_MASK(sv, sub_) do { if (needmask) { _Pragma("unroll") for (int r = 0; r < 16; ++r) { const int kl_ = (sub_) * 32 + ((r < 8) ? (8 * g2 + r) : (16 + 8 * g2 + (r - 8))); \
;           if ((pki[kl_] >> 6) > (((int)qposf) >> 6)) sv[r] = -__builtin_inff(); } } } while (0)
; template <bool DIFF>
; DI void attn_phase(const AttnArgs& a, char* lds) {
;     ...
;       if (nxt) {
;         const int t2 = tid_pinned();
;         const u32 kofs = KOFS(t2), vofs = VOFS(t2);
;         const u32 ko2 = kofs + (u32)(t + 1) * 64u * (u32)a.ldk;
; #pragma unroll
;         for (int i = 0; i < NKR; ++i) GLDS16(a.K + ko2 + i * 64, nb + wave * 1024 + 8192 * i);
;         const u32 vo2 = vofs + (u32)(t + 1) * (u32)(DV * 64);
; #pragma unroll
;         for (int i = 0; i < NVR; ++i) GLDS16(a.VT + vo2 + i * 4096, nb + KBYTES + wave * 1024 + 8192 * i);
;         if (wave == 0) { const int l4 = (t + 1) * 64 + (t2 & 63); GLDS4(a.pos + l4, nb + KBYTES + VBYTES); GLDS4(a.posf + l4, nb + KBYTES + VBYTES + 256); }
;       }
;     ...
;         for (int ds = 0; ds < NDS; ++ds) kf[ds] = *(const bf16x8*)(sb + koffb + (ds >> 2) * 8192 + ((((ds & 3) * 2) ^ kx) << 4));
;         f32x16 s0, s1;
;         s0 = MFMA(kf[0], qf[0], zero16());
; #pragma unroll
;         for (int ds = 1; ds < NDS; ++ds) s0 = MFMA(kf[ds], qf[ds], s0);
; #pragma unroll
;         for (int ds = 0; ds < NDS; ++ds) kf[ds] = *(const bf16x8*)(sb + koffb + 4096 + (ds >> 2) * 8192 + ((((ds & 3) * 2) ^ kx) << 4));
;         __builtin_amdgcn_sched_barrier(0);
;         {
;           s1 = MFMA(kf[0], qf[0], zero16());
; #pragma unroll
;           for (int ds = 1; ds < NDS; ++ds) s1 = MFMA(kf[ds], qf[ds], s1);
;           DIFF_ALIBI(s0, 0);
;           DIFF_MASK(s0, 0);
.Ldiff_nd0:
	s_waitcnt lgkmcnt(8)
	v_mfma_f32_32x32x16_bf16 v[160:175], v[12:15], v[180:183], v[160:175]
	ds_read_b128 v[12:15], v147 offset:4096
	s_waitcnt lgkmcnt(8)
	v_mfma_f32_32x32x16_bf16 v[160:175], v[228:231], v[184:187], v[160:175]
	ds_read_b128 v[228:231], v148 offset:4096
	s_waitcnt lgkmcnt(8)
	v_mfma_f32_32x32x16_bf16 v[160:175], v[232:235], v[188:191], v[160:175]
	ds_read_b128 v[232:235], v144 offset:4096
	s_waitcnt lgkmcnt(8)
	v_mfma_f32_32x32x16_bf16 v[160:175], v[236:239], v[192:195], v[160:175]
	ds_read_b128 v[236:239], v146 offset:12288
	s_cbranch_vccnz .Ldiff_nd1
	s_add_i32 m0, s86, 0x2000
	s_add_u32 s88, s98, s42
	s_addc_u32 s89, s99, s43
	global_load_lds_dwordx4 v209, s[88:89]
.Ldiff_nd1:
	s_waitcnt lgkmcnt(8)
	v_mfma_f32_32x32x16_bf16 v[160:175], v[240:243], v[196:199], v[160:175]
	ds_read_b128 v[240:243], v147 offset:12288
	s_waitcnt lgkmcnt(8)
	v_mfma_f32_32x32x16_bf16 v[160:175], v[244:247], v[200:203], v[160:175]
	ds_read_b128 v[244:247], v148 offset:12288
	s_waitcnt lgkmcnt(8)
	v_mfma_f32_32x32x16_bf16 v[160:175], v[4:7], v[204:207], v[160:175]
	s_waitcnt lgkmcnt(6)
	v_mfma_f32_32x32x16_bf16 v[144:159], v[8:11], v[176:179], 0
	v_add_u32_e32 v253, 0x10100, v227
	ds_read_b128 v[4:7], v253
	ds_read_b128 v[8:11], v253 offset:16
	s_and_b64 vcc, exec, s[8:9]
	s_waitcnt lgkmcnt(1)
	v_sub_f32_e32 v4, v221, v4
	v_sub_f32_e32 v5, v221, v5
	v_mfma_f32_32x32x16_bf16 v[144:159], v[12:15], v[180:183], v[144:159]
	v_sub_f32_e32 v6, v221, v6
	v_sub_f32_e32 v7, v221, v7
	s_waitcnt lgkmcnt(0)
	v_sub_f32_e32 v12, v221, v8
	v_sub_f32_e32 v13, v221, v9
	v_sub_f32_e32 v14, v221, v10
	v_sub_f32_e32 v15, v221, v11
	v_mfma_f32_32x32x16_bf16 v[144:159], v[228:231], v[184:187], v[144:159]
	s_cmp_lg_u64 s[66:67], 0
	s_cbranch_scc1 .Ldiff_nd2
	s_add_i32 m0, s86, 0x4000
	s_add_u32 s88, s98, s56
	s_addc_u32 s89, s99, s57
	global_load_lds_dwordx4 v209, s[88:89]
.Ldiff_nd2:
	v_fma_f32 v11, -v223, |v4|, v160
	v_fma_f32 v9, -v223, |v5|, v161
	v_fma_f32 v10, -v223, |v6|, v162
	v_fma_f32 v8, -v223, |v7|, v163
	v_fma_f32 v7, -v223, |v12|, v164
	v_fma_f32 v6, -v223, |v13|, v165
	v_fma_f32 v5, -v223, |v14|, v166
	v_mfma_f32_32x32x16_bf16 v[144:159], v[232:235], v[188:191], v[144:159]
	v_fma_f32 v4, -v223, |v15|, v167
	ds_read_b128 v[12:15], v253 offset:64
	ds_read_b128 v[160:163], v253 offset:80
	s_waitcnt lgkmcnt(1)
	v_sub_f32_e32 v12, v221, v12
	v_mfma_f32_32x32x16_bf16 v[144:159], v[236:239], v[192:195], v[144:159]
	v_sub_f32_e32 v13, v221, v13
	v_sub_f32_e32 v14, v221, v14
	v_sub_f32_e32 v15, v221, v15
	s_waitcnt lgkmcnt(0)
	v_sub_f32_e32 v165, v221, v160
	v_sub_f32_e32 v166, v221, v161
	v_sub_f32_e32 v167, v221, v162
	v_sub_f32_e32 v163, v221, v163
	v_mfma_f32_32x32x16_bf16 v[144:159], v[240:243], v[196:199], v[144:159]
	s_cmp_lg_u64 s[66:67], 0
	s_cbranch_scc1 .Ldiff_nd3
	s_add_i32 m0, s86, 0x6000
	s_add_u32 s88, s98, s58
	s_addc_u32 s89, s99, s59
	global_load_lds_dwordx4 v209, s[88:89]
.Ldiff_nd3:
	v_mov_b32_e32 v209, 0x6000
	s_nop 0
	v_fma_f32 v164, -v223, |v12|, v168
	v_fma_f32 v162, -v223, |v13|, v169
	v_fma_f32 v160, -v223, |v14|, v170
	v_fma_f32 v161, -v223, |v15|, v171
	v_fma_f32 v15, -v223, |v165|, v172
	v_mfma_f32_32x32x16_bf16 v[144:159], v[244:247], v[200:203], v[144:159]
	v_fma_f32 v14, -v223, |v166|, v173
	v_fma_f32 v13, -v223, |v167|, v174
	v_fma_f32 v12, -v223, |v163|, v175
	v_add_u32_e32 v163, s1, v252
	v_mfma_f32_32x32x16_bf16 v[144:159], v[248:251], v[204:207], v[144:159]
	s_cbranch_vccnz .LBB0_605
	ds_read_b128 v[166:169], v163
	v_add_u32_e32 v165, 0x10050, v227
	ds_read_b128 v[170:173], v165
	s_waitcnt lgkmcnt(1)
	v_ashrrev_i32_e32 v165, 6, v166
	v_ashrrev_i32_e32 v166, 6, v167
	v_cmp_le_i32_e32 vcc, v165, v224
	v_ashrrev_i32_e32 v165, 6, v168
	s_nop 0
	v_cndmask_b32_e32 v11, v216, v11, vcc
	v_cmp_le_i32_e32 vcc, v166, v224
	v_add_u32_e32 v166, 0x10010, v227
	s_nop 0
	v_cndmask_b32_e32 v9, v216, v9, vcc
	v_cmp_le_i32_e32 vcc, v165, v224
	v_ashrrev_i32_e32 v165, 6, v169
	ds_read_b128 v[166:169], v166
	v_cndmask_b32_e32 v10, v216, v10, vcc
	v_cmp_le_i32_e32 vcc, v165, v224
	v_add_u32_e32 v165, 0x10040, v227
	ds_read_b128 v[228:231], v165
	s_waitcnt lgkmcnt(1)
	v_ashrrev_i32_e32 v165, 6, v166
	v_cndmask_b32_e32 v8, v216, v8, vcc
	v_cmp_le_i32_e32 vcc, v165, v224
	v_ashrrev_i32_e32 v165, 6, v167
	s_nop 0
	v_cndmask_b32_e32 v7, v216, v7, vcc
	v_cmp_le_i32_e32 vcc, v165, v224
	v_ashrrev_i32_e32 v165, 6, v168
	s_nop 0
	v_cndmask_b32_e32 v6, v216, v6, vcc
	v_cmp_le_i32_e32 vcc, v165, v224
	v_ashrrev_i32_e32 v165, 6, v169
	s_nop 0
	v_cndmask_b32_e32 v5, v216, v5, vcc
	v_cmp_le_i32_e32 vcc, v165, v224
	s_waitcnt lgkmcnt(0)
	v_ashrrev_i32_e32 v165, 6, v228
	v_cndmask_b32_e32 v4, v216, v4, vcc
	v_cmp_le_i32_e32 vcc, v165, v224
	v_ashrrev_i32_e32 v165, 6, v229
	s_nop 0
	v_cndmask_b32_e32 v164, v216, v164, vcc
	v_cmp_le_i32_e32 vcc, v165, v224
	v_ashrrev_i32_e32 v165, 6, v230
	s_nop 0
	v_cndmask_b32_e32 v162, v216, v162, vcc
	v_cmp_le_i32_e32 vcc, v165, v224
	v_ashrrev_i32_e32 v165, 6, v231
	s_nop 0
	v_cndmask_b32_e32 v160, v216, v160, vcc
	v_cmp_le_i32_e32 vcc, v165, v224
	v_ashrrev_i32_e32 v165, 6, v170
	s_nop 0
	v_cndmask_b32_e32 v161, v216, v161, vcc
	v_cmp_le_i32_e32 vcc, v165, v224
	v_ashrrev_i32_e32 v165, 6, v171
	s_nop 0
	v_cndmask_b32_e32 v15, v216, v15, vcc
	v_cmp_le_i32_e32 vcc, v165, v224
	v_ashrrev_i32_e32 v165, 6, v172
	s_nop 0
	v_cndmask_b32_e32 v14, v216, v14, vcc
	v_cmp_le_i32_e32 vcc, v165, v224
	v_ashrrev_i32_e32 v165, 6, v173
	s_nop 0
	v_cndmask_b32_e32 v13, v216, v13, vcc
	v_cmp_le_i32_e32 vcc, v165, v224
	s_nop 1
	v_cndmask_b32_e32 v12, v216, v12, vcc
; #define MFMA(a, b, c) __builtin_amdgcn_mfma_f32_32x32x16_bf16((a), (b), (c), 0, 0, 0)
; #define GLDS16(g, l) __builtin_amdgcn_global_load_lds((const unsigned*)(g), (unsigned*)(l), 16, 0, 0)
; #define GLDS4(g, l) __builtin_amdgcn_global_load_lds((const unsigned*)(g), (unsigned*)(l), 4, 0, 0)
; DI u32 pk2(float a, float b) { f2_t v = {a, b}; bf2_t r = __builtin_convertvector(v, bf2_t); return __builtin_bit_cast(u32, r); }
; #define DIFF_MASK(sv, sub_) do { if (needmask) { _Pragma("unroll") for (int r = 0; r < 16; ++r) { const int kl_ = (sub_) * 32 + ((r < 8) ? (8 * g2 + r) : (16 + 8 * g2 + (r - 8))); \
;           if ((pki[kl_] >> 6) > (((int)qposf) >> 6)) sv[r] = -__builtin_inff(); } } } while (0)
; template <bool DIFF>
; DI void attn_phase(const AttnArgs& a, char* lds) {
;     ...
;         for (int i = 0; i < NKR; ++i) GLDS16(a.K + ko2 + i * 64, nb + wave * 1024 + 8192 * i);
;         const u32 vo2 = vofs + (u32)(t + 1) * (u32)(DV * 64);
; #pragma unroll
;         for (int i = 0; i < NVR; ++i) GLDS16(a.VT + vo2 + i * 4096, nb + KBYTES + wave * 1024 + 8192 * i);
;         if (wave == 0) { const int l4 = (t + 1) * 64 + (t2 & 63); GLDS4(a.pos + l4, nb + KBYTES + VBYTES); GLDS4(a.posf + l4, nb + KBYTES + VBYTES + 256); }
;     ...
;           bf16x8 vf[NM];
; #pragma unroll
;           for (int s2 = 0; s2 < 2; ++s2) {
; #pragma unroll
;             for (int m = 0; m < NM; ++m) vf[m] = *(const bf16x8*)(sb + voffb + m * 4096 + (((2 * s2) ^ vx) << 4));
;             u32x4 pw;
;             pw[0] = pk2(s0[8 * s2], s0[8 * s2 + 1]); pw[1] = pk2(s0[8 * s2 + 2], s0[8 * s2 + 3]);
;             pw[2] = pk2(s0[8 * s2 + 4], s0[8 * s2 + 5]); pw[3] = pk2(s0[8 * s2 + 6], s0[8 * s2 + 7]);
;             const bf16x8 pf = __builtin_bit_cast(bf16x8, pw);
; #pragma unroll
;             for (int m = 0; m < NM; ++m) o[m] = MFMA(vf[m], pf, o[m]);
;           }
;           DIFF_ALIBI(s1, 1);
;           DIFF_MASK(s1, 1);
.LBB0_605:
	v_exp_f32_e32 v11, v11
	v_exp_f32_e32 v9, v9
	v_exp_f32_e32 v10, v10
	v_exp_f32_e32 v8, v8
	v_bitop3_b32 v0, v0, v3, 7 bitop3:0x78
	v_add_f32_e32 v3, 0, v11
	v_exp_f32_e32 v165, v7
	v_add_f32_e32 v3, v9, v3
	v_exp_f32_e32 v166, v6
	v_add_f32_e32 v3, v10, v3
	v_exp_f32_e32 v167, v5
	v_add_f32_e32 v3, v8, v3
	v_exp_f32_e32 v168, v4
	v_add_f32_e32 v3, v165, v3
	v_exp_f32_e32 v164, v164
	v_lshlrev_b32_e32 v2, 7, v2
	v_add_f32_e32 v3, v166, v3
	v_exp_f32_e32 v169, v162
	v_and_b32_e32 v2, 0xf80, v2
	v_add_f32_e32 v3, v167, v3
	v_exp_f32_e32 v170, v160
	v_add_f32_e32 v3, v168, v3
	v_exp_f32_e32 v171, v161
	v_add_f32_e32 v3, v164, v3
	v_exp_f32_e32 v15, v15
	v_add_f32_e32 v3, v169, v3
	v_exp_f32_e32 v14, v14
	v_add_f32_e32 v3, v170, v3
	v_exp_f32_e32 v172, v13
	v_add_f32_e32 v3, v171, v3
	v_exp_f32_e32 v173, v12
	v_add_f32_e32 v3, v15, v3
	v_add_f32_e32 v3, v14, v3
	v_add_f32_e32 v3, v172, v3
	v_add_f32_e32 v3, v173, v3
	v_add_f32_e32 v162, v226, v3
	v_add_u32_e32 v160, s84, v2
	v_lshlrev_b32_e32 v161, 4, v0
	v_add_u32_e32 v0, v160, v161
	v_cvt_pk_bf16_f32 v6, v11, v9
	v_cvt_pk_bf16_f32 v7, v10, v8
	v_cvt_pk_bf16_f32 v8, v165, v166
	v_cvt_pk_bf16_f32 v9, v167, v168
	v_cvt_pk_bf16_f32 v10, v164, v169
	v_cvt_pk_bf16_f32 v11, v170, v171
	v_cvt_pk_bf16_f32 v12, v15, v14
	v_cvt_pk_bf16_f32 v13, v172, v173
	v_add_u32_e32 v14, 0x10180, v227
	v_xad_u32 v15, v161, 32, v160
	ds_read_b128 v[164:167], v14
	ds_read_b128 v[168:171], v14 offset:16
	ds_read_b128 v[172:175], v14 offset:64
	ds_read_b128 v[248:251], v14 offset:80
	ds_read_b128 v[2:5], v0 offset:32768
	ds_read_b128 v[228:231], v0 offset:36864
	ds_read_b128 v[232:235], v0 offset:40960
	ds_read_b128 v[236:239], v0 offset:45056
	ds_read_b128 v[240:243], v0 offset:49152
	ds_read_b128 v[244:247], v0 offset:53248
	s_and_b64 vcc, exec, s[8:9]
	s_waitcnt lgkmcnt(5)
	v_mfma_f32_32x32x16_bf16 v[128:143], v[2:5], v[6:9], v[128:143]
	ds_read_b128 v[2:5], v0 offset:57344
	v_sub_f32_e32 v164, v221, v164
	v_sub_f32_e32 v165, v221, v165
	v_fma_f32 v164, -v223, |v164|, v144
	v_fma_f32 v165, -v223, |v165|, v145
	s_waitcnt lgkmcnt(5)
	v_mfma_f32_32x32x16_bf16 v[112:127], v[228:231], v[6:9], v[112:127]
	ds_read_b128 v[228:231], v0 offset:61440
	v_sub_f32_e32 v166, v221, v166
	v_sub_f32_e32 v167, v221, v167
	v_fma_f32 v166, -v223, |v166|, v146
	v_fma_f32 v167, -v223, |v167|, v147
	s_cmp_lg_u64 s[66:67], 0
	s_cbranch_scc1 .Ldiff_nd4
	s_add_i32 m0, s86, 0x8000
	s_nop 0
	global_load_lds_dwordx4 v255, s[52:53]
.Ldiff_nd4:
	s_waitcnt lgkmcnt(5)
	v_mfma_f32_32x32x16_bf16 v[96:111], v[232:235], v[6:9], v[96:111]
	ds_read_b128 v[232:235], v15 offset:32768
	v_sub_f32_e32 v168, v221, v168
	v_sub_f32_e32 v169, v221, v169
	v_fma_f32 v168, -v223, |v168|, v148
	v_fma_f32 v169, -v223, |v169|, v149
	s_waitcnt lgkmcnt(5)
	v_mfma_f32_32x32x16_bf16 v[80:95], v[236:239], v[6:9], v[80:95]
	ds_read_b128 v[236:239], v15 offset:36864
	v_sub_f32_e32 v170, v221, v170
	v_sub_f32_e32 v171, v221, v171
	v_fma_f32 v170, -v223, |v170|, v150
	v_fma_f32 v171, -v223, |v171|, v151
	s_cmp_lg_u64 s[66:67], 0
	s_cbranch_scc1 .Ldiff_nd5
	s_add_i32 m0, s86, 0xa000
	s_add_u32 s88, s52, s60
	s_addc_u32 s89, s53, s61
	global_load_lds_dwordx4 v255, s[88:89]
.Ldiff_nd5:
	s_waitcnt lgkmcnt(5)
	v_mfma_f32_32x32x16_bf16 v[64:79], v[240:243], v[6:9], v[64:79]
	ds_read_b128 v[240:243], v15 offset:40960
	v_sub_f32_e32 v172, v221, v172
	v_sub_f32_e32 v173, v221, v173
	v_fma_f32 v172, -v223, |v172|, v152
	v_fma_f32 v173, -v223, |v173|, v153
	s_waitcnt lgkmcnt(5)
	v_mfma_f32_32x32x16_bf16 v[48:63], v[244:247], v[6:9], v[48:63]
	ds_read_b128 v[244:247], v15 offset:45056
	v_sub_f32_e32 v174, v221, v174
	v_sub_f32_e32 v175, v221, v175
	v_fma_f32 v174, -v223, |v174|, v154
	v_fma_f32 v175, -v223, |v175|, v155
	s_cmp_lg_u64 s[66:67], 0
	s_cbranch_scc1 .Ldiff_nd6
	s_add_i32 m0, s86, 0xc000
	s_add_u32 s88, s52, s62
	s_addc_u32 s89, s53, s63
	global_load_lds_dwordx4 v255, s[88:89]
.Ldiff_nd6:
	s_waitcnt lgkmcnt(5)
	v_mfma_f32_32x32x16_bf16 v[32:47], v[2:5], v[6:9], v[32:47]
	ds_read_b128 v[2:5], v15 offset:49152
	v_sub_f32_e32 v248, v221, v248
	v_sub_f32_e32 v249, v221, v249
	v_fma_f32 v248, -v223, |v248|, v156
	v_fma_f32 v249, -v223, |v249|, v157
	s_waitcnt lgkmcnt(5)
	v_mfma_f32_32x32x16_bf16 v[16:31], v[228:231], v[6:9], v[16:31]
	ds_read_b128 v[228:231], v15 offset:53248
	v_sub_f32_e32 v250, v221, v250
	v_sub_f32_e32 v251, v221, v251
	v_fma_f32 v250, -v223, |v250|, v158
	v_fma_f32 v251, -v223, |v251|, v159
	s_cmp_lg_u64 s[66:67], 0
	s_cbranch_scc1 .Ldiff_nd7
	s_add_i32 m0, s86, 0xe000
	s_add_u32 s88, s52, s64
	s_addc_u32 s89, s53, s65
	global_load_lds_dwordx4 v255, s[88:89]
.Ldiff_nd7:
	s_cbranch_vccnz .Ldiff_nomask1
	ds_read_b128 v[146:149], v163 offset:128
	s_waitcnt lgkmcnt(0)
	v_ashrrev_i32_e32 v144, 6, v146
	v_cmp_le_i32_e32 vcc, v144, v224
	v_ashrrev_i32_e32 v144, 6, v147
	s_nop 0
	v_cndmask_b32_e32 v164, v216, v164, vcc
	v_cmp_le_i32_e32 vcc, v144, v224
	v_ashrrev_i32_e32 v144, 6, v148
	s_nop 0
	v_cndmask_b32_e32 v165, v216, v165, vcc
	v_cmp_le_i32_e32 vcc, v144, v224
	v_ashrrev_i32_e32 v144, 6, v149
	s_nop 0
	v_cndmask_b32_e32 v166, v216, v166, vcc
	v_cmp_le_i32_e32 vcc, v144, v224
	v_add_u32_e32 v144, 0x10090, v227
	ds_read_b128 v[146:149], v144
	v_cndmask_b32_e32 v167, v216, v167, vcc
	s_waitcnt lgkmcnt(0)
	v_ashrrev_i32_e32 v144, 6, v146
	v_cmp_le_i32_e32 vcc, v144, v224
	v_ashrrev_i32_e32 v144, 6, v147
	s_nop 0
	v_cndmask_b32_e32 v168, v216, v168, vcc
	v_cmp_le_i32_e32 vcc, v144, v224
	v_ashrrev_i32_e32 v144, 6, v148
	s_nop 0
	v_cndmask_b32_e32 v169, v216, v169, vcc
	v_cmp_le_i32_e32 vcc, v144, v224
	v_ashrrev_i32_e32 v144, 6, v149
	s_nop 0
	v_cndmask_b32_e32 v170, v216, v170, vcc
	v_cmp_le_i32_e32 vcc, v144, v224
	v_add_u32_e32 v144, 0x100c0, v227
	ds_read_b128 v[146:149], v144
	v_cndmask_b32_e32 v171, v216, v171, vcc
	s_waitcnt lgkmcnt(0)
	v_ashrrev_i32_e32 v144, 6, v146
	v_cmp_le_i32_e32 vcc, v144, v224
	v_ashrrev_i32_e32 v144, 6, v147
	s_nop 0
	v_cndmask_b32_e32 v172, v216, v172, vcc
	v_cmp_le_i32_e32 vcc, v144, v224
	v_ashrrev_i32_e32 v144, 6, v148
	s_nop 0
	v_cndmask_b32_e32 v173, v216, v173, vcc
	v_cmp_le_i32_e32 vcc, v144, v224
	v_ashrrev_i32_e32 v144, 6, v149
	s_nop 0
	v_cndmask_b32_e32 v174, v216, v174, vcc
	v_cmp_le_i32_e32 vcc, v144, v224
	v_add_u32_e32 v144, 0x100d0, v227
	ds_read_b128 v[146:149], v144
	v_cndmask_b32_e32 v175, v216, v175, vcc
	s_waitcnt lgkmcnt(0)
	v_ashrrev_i32_e32 v144, 6, v146
	v_cmp_le_i32_e32 vcc, v144, v224
	v_ashrrev_i32_e32 v144, 6, v147
	s_nop 0
	v_cndmask_b32_e32 v248, v216, v248, vcc
	v_cmp_le_i32_e32 vcc, v144, v224
	v_ashrrev_i32_e32 v144, 6, v148
	s_nop 0
	v_cndmask_b32_e32 v249, v216, v249, vcc
	v_cmp_le_i32_e32 vcc, v144, v224
	v_ashrrev_i32_e32 v144, 6, v149
	s_nop 0
	v_cndmask_b32_e32 v250, v216, v250, vcc
	v_cmp_le_i32_e32 vcc, v144, v224
	s_nop 1
	v_cndmask_b32_e32 v251, v216, v251, vcc
